# P3: workgroups sharing a CU walk their unit list in opposite directions (GEMM tiles of one overlap the small latency-bound units of the other)
# baseline (speedup 1.0000x reference)
; static __device__ __forceinline__ KP lp(KP q) { asm volatile("" : "+s"(q)); return q; }
; __global__ void __launch_bounds__(256, 2) trunk_megakernel(Params pk) {
;     ...
;     for (int rep = 0; rep < REP_P3; ++rep)
;     for (int u = B; u < 816 + 1088 + 2176 + 2176; u += G) {
;       if (u < 816) p3_qproj(lp(p), u, smem, l);
;       else if (u < 1904) p3_kvproj(lp(p), u - 816, smem);
;       else if (u < 4080) p3_kpe(lp(p), u - 1904);
;       else lru_unit(lp(p), l, u - 4080, 1, smem);
;     }
.LBB0_502:
	s_or_b64 exec, exec, s[6:7]
	v_readlane_b32 s2, v255, 4
	v_readlane_b32 s3, v255, 5
	s_lshl_b32 s77, s76, 11
	s_andn2_b64 vcc, exec, s[2:3]
	s_mov_b32 s18, s72
	v_readlane_b32 s19, v255, 16
	s_mov_b32 s21, s72
	s_lshr_b32 s82, s72, 3
	s_lshr_b32 s83, s72, 8
	s_xor_b32 s82, s82, s83
	s_and_b32 s82, s82, 1
	s_mov_b32 s82, s61
	s_cbranch_scc0 .Lrev_p3_fwd
	s_sub_i32 s83, 0x186f, s72
	s_mov_b32 s82, 0
.Lrev_p3_k:
	s_add_i32 s82, s82, s61
	s_cmp_le_i32 s82, s83
	s_cbranch_scc1 .Lrev_p3_k
	s_sub_i32 s82, s82, s61
	s_add_i32 s21, s21, s82
	s_add_i32 s19, s19, s82
	s_add_i32 s18, s18, s82
	s_sub_i32 s82, 0, s61
.Lrev_p3_fwd:
	s_waitcnt lgkmcnt(0)
	s_barrier
	s_cbranch_vccz .LBB0_516

; __global__ void __launch_bounds__(256, 2) trunk_megakernel(Params pk) {
;     ...
;     for (int u = B; u < 816 + 1088 + 2176 + 2176; u += G) {
.LBB0_515:
	s_add_i32 s21, s21, s82
	s_add_i32 s19, s19, s82
	s_add_i32 s18, s18, s82
	s_cmpk_gt_i32 s21, 0x186f
	s_cbranch_scc1 .LBB0_503
	s_cmp_lt_i32 s21, 0
	s_cbranch_scc1 .LBB0_503
